# 64-byte alignment of the 7 hand-written K-loop heads (gemm_in/w_out/w_down P and Q loops, gemm_up loop) on top of v47
# baseline (speedup 1.0000x reference)
.Lgxi_go:
	s_cmp_eq_u64 s[4:5], 0
	s_cbranch_scc1 .Lgxi_q
	.p2align 6

.Lgxi_pcb:
	s_add_u32 s99, s99, 0xd000
	s_cmp_eq_u32 s99, 0x27000
	s_cselect_b32 s99, 0, s99
	s_branch .Lg160i_epi
	.p2align 6

.LBB0_830:
	s_mul_hi_i32 s42, s48, 0x2e8ba2e9
	s_lshr_b32 s43, s42, 31
	s_ashr_i32 s42, s42, 5
	s_add_i32 s42, s42, s43
	s_lshl_b32 s42, s42, 3
	s_and_b32 s43, s48, 7
	s_or_b32 s62, s42, s43
	s_ashr_i32 s42, s48, 3
	s_mul_hi_i32 s43, s42, 0x2e8ba2e9
	s_lshr_b32 s48, s43, 31
	s_ashr_i32 s43, s43, 2
	s_add_i32 s43, s43, s48
	s_mul_i32 s43, s43, 22
	s_sub_i32 s58, s42, s43
	s_ashr_i32 s63, s62, 31
	s_ashr_i32 s59, s58, 31
	s_lshl_b64 s[42:43], s[62:63], 19
	s_lshl_b64 s[48:49], s[58:59], 19
	v_readfirstlane_b32 s59, v178
	v_add_u32_e32 v4, 0x8000, v178
	v_lshl_add_u64 v[0:1], v[132:133], 0, s[42:43]
	s_mov_b32 m0, s59
	v_readfirstlane_b32 s59, v4
	v_add_u32_e32 v6, 0x2000, v178
	v_lshl_add_u64 v[2:3], v[134:135], 0, s[48:49]
	global_load_lds_dwordx4 v[0:1], off
	s_mov_b32 m0, s59
	s_mov_b64 s[96:97], 0x20000
	v_readfirstlane_b32 s59, v6
	v_add_u32_e32 v6, 0xa000, v178
	global_load_lds_dwordx4 v[2:3], off
	v_lshl_add_u64 v[4:5], v[0:1], 0, s[96:97]
	s_mov_b32 m0, s59
	v_readfirstlane_b32 s59, v6
	v_add_u32_e32 v6, 0x4000, v178
	global_load_lds_dwordx4 v[4:5], off
	v_lshl_add_u64 v[4:5], v[2:3], 0, s[96:97]
	s_mov_b32 m0, s59
	v_readfirstlane_b32 s59, v6
	v_add_u32_e32 v6, 0xc000, v178
	global_load_lds_dwordx4 v[4:5], off
	v_lshl_add_u64 v[4:5], v[0:1], 0, s[74:75]
	s_mov_b32 m0, s59
	v_readfirstlane_b32 s59, v6
	global_load_lds_dwordx4 v[4:5], off
	v_lshl_add_u64 v[4:5], v[2:3], 0, s[74:75]
	s_mov_b32 m0, s59
	s_mov_b64 s[96:97], 0x60000
	global_load_lds_dwordx4 v[4:5], off
	v_add_u32_e32 v4, 0x6000, v178
	v_lshl_add_u64 v[0:1], v[0:1], 0, s[96:97]
	v_readfirstlane_b32 s59, v4
	s_mov_b32 m0, s59
	s_mov_b64 s[72:73], 0x20000
	global_load_lds_dwordx4 v[0:1], off
	v_lshl_add_u64 v[0:1], v[2:3], 0, s[96:97]
	v_add_u32_e32 v2, 0xe000, v178
	v_lshl_add_u64 v[174:175], v[170:171], 0, s[48:49]
	v_readfirstlane_b32 s59, v2
	s_mov_b32 m0, s59
	v_lshl_add_u64 v[176:177], v[172:173], 0, s[42:43]
	global_load_lds_dwordx4 v[0:1], off
	v_mov_b32_e32 v0, 0
	s_mov_b32 s42, 0
	s_mov_b64 s[96:97], 0
	v_mov_b32_e32 v1, v0
	v_mov_b32_e32 v2, v0
	v_mov_b32_e32 v3, v0
	v_mov_b32_e32 v4, v0
	v_mov_b32_e32 v5, v0
	v_mov_b32_e32 v6, v0
	v_mov_b32_e32 v7, v0
	v_mov_b32_e32 v8, v0
	v_mov_b32_e32 v9, v0
	v_mov_b32_e32 v10, v0
	v_mov_b32_e32 v11, v0
	v_mov_b32_e32 v12, v0
	v_mov_b32_e32 v13, v0
	v_mov_b32_e32 v14, v0
	v_mov_b32_e32 v15, v0
	v_mov_b32_e32 v16, v0
	v_mov_b32_e32 v17, v0
	v_mov_b32_e32 v18, v0
	v_mov_b32_e32 v19, v0
	v_mov_b32_e32 v20, v0
	v_mov_b32_e32 v21, v0
	v_mov_b32_e32 v22, v0
	v_mov_b32_e32 v23, v0
	v_mov_b32_e32 v24, v0
	v_mov_b32_e32 v25, v0
	v_mov_b32_e32 v26, v0
	v_mov_b32_e32 v27, v0
	v_mov_b32_e32 v28, v0
	v_mov_b32_e32 v29, v0
	v_mov_b32_e32 v30, v0
	v_mov_b32_e32 v31, v0
	v_mov_b32_e32 v32, v0
	v_mov_b32_e32 v33, v0
	v_mov_b32_e32 v34, v0
	v_mov_b32_e32 v35, v0
	v_mov_b32_e32 v36, v0
	v_mov_b32_e32 v37, v0
	v_mov_b32_e32 v38, v0
	v_mov_b32_e32 v39, v0
	v_mov_b32_e32 v40, v0
	v_mov_b32_e32 v41, v0
	v_mov_b32_e32 v42, v0
	v_mov_b32_e32 v43, v0
	v_mov_b32_e32 v44, v0
	v_mov_b32_e32 v45, v0
	v_mov_b32_e32 v46, v0
	v_mov_b32_e32 v47, v0
	v_mov_b32_e32 v48, v0
	v_mov_b32_e32 v49, v0
	v_mov_b32_e32 v50, v0
	v_mov_b32_e32 v51, v0
	v_mov_b32_e32 v52, v0
	v_mov_b32_e32 v53, v0
	v_mov_b32_e32 v54, v0
	v_mov_b32_e32 v55, v0
	v_mov_b32_e32 v56, v0
	v_mov_b32_e32 v57, v0
	v_mov_b32_e32 v58, v0
	v_mov_b32_e32 v59, v0
	v_mov_b32_e32 v60, v0
	v_mov_b32_e32 v61, v0
	v_mov_b32_e32 v62, v0
	v_mov_b32_e32 v63, v0
	v_mov_b32_e32 v64, v0
	v_mov_b32_e32 v65, v0
	v_mov_b32_e32 v66, v0
	v_mov_b32_e32 v67, v0
	v_mov_b32_e32 v68, v0
	v_mov_b32_e32 v69, v0
	v_mov_b32_e32 v70, v0
	v_mov_b32_e32 v71, v0
	v_mov_b32_e32 v72, v0
	v_mov_b32_e32 v73, v0
	v_mov_b32_e32 v74, v0
	v_mov_b32_e32 v75, v0
	v_mov_b32_e32 v76, v0
	v_mov_b32_e32 v77, v0
	v_mov_b32_e32 v78, v0
	v_mov_b32_e32 v79, v0
	v_mov_b32_e32 v80, v0
	v_mov_b32_e32 v81, v0
	v_mov_b32_e32 v82, v0
	v_mov_b32_e32 v83, v0
	v_mov_b32_e32 v84, v0
	v_mov_b32_e32 v85, v0
	v_mov_b32_e32 v86, v0
	v_mov_b32_e32 v87, v0
	v_mov_b32_e32 v88, v0
	v_mov_b32_e32 v89, v0
	v_mov_b32_e32 v90, v0
	v_mov_b32_e32 v91, v0
	v_mov_b32_e32 v92, v0
	v_mov_b32_e32 v93, v0
	v_mov_b32_e32 v94, v0
	v_mov_b32_e32 v95, v0
	v_mov_b32_e32 v96, v0
	v_mov_b32_e32 v97, v0
	v_mov_b32_e32 v98, v0
	v_mov_b32_e32 v99, v0
	v_mov_b32_e32 v100, v0
	v_mov_b32_e32 v101, v0
	v_mov_b32_e32 v102, v0
	v_mov_b32_e32 v103, v0
	v_mov_b32_e32 v104, v0
	v_mov_b32_e32 v105, v0
	v_mov_b32_e32 v106, v0
	v_mov_b32_e32 v107, v0
	v_mov_b32_e32 v108, v0
	v_mov_b32_e32 v109, v0
	v_mov_b32_e32 v110, v0
	v_mov_b32_e32 v111, v0
	v_mov_b32_e32 v112, v0
	v_mov_b32_e32 v113, v0
	v_mov_b32_e32 v114, v0
	v_mov_b32_e32 v115, v0
	v_mov_b32_e32 v116, v0
	v_mov_b32_e32 v117, v0
	v_mov_b32_e32 v118, v0
	v_mov_b32_e32 v119, v0
	v_mov_b32_e32 v120, v0
	v_mov_b32_e32 v121, v0
	v_mov_b32_e32 v122, v0
	v_mov_b32_e32 v123, v0
	v_mov_b32_e32 v124, v0
	v_mov_b32_e32 v125, v0
	v_mov_b32_e32 v126, v0
	v_mov_b32_e32 v127, v0
	v_readfirstlane_b32 s99, v178
	v_add_u32_e32 v229, 0x10000, v178
	s_nop 0
	v_readfirstlane_b32 s98, v229
	s_nop 3
	s_add_u32 s48, s96, s78
	s_addc_u32 s49, s97, s79
	v_lshl_add_u64 v[220:221], v[176:177], 0, s[48:49]
	s_mov_b32 m0, s98
	s_nop 0
	global_load_lds_dwordx4 v[220:221], off
	s_add_u32 s48, s96, 0x560080
	s_addc_u32 s49, s97, 0
	v_lshl_add_u64 v[220:221], v[174:175], 0, s[48:49]
	s_add_u32 m0, s98, 0x8000
	s_nop 0
	global_load_lds_dwordx4 v[220:221], off
	s_add_u32 s48, s96, s80
	s_addc_u32 s49, s97, s81
	v_lshl_add_u64 v[220:221], v[176:177], 0, s[48:49]
	s_add_u32 m0, s98, 0x2000
	s_nop 0
	global_load_lds_dwordx4 v[220:221], off
	s_add_u32 s48, s96, 0x580080
	s_addc_u32 s49, s97, 0
	v_lshl_add_u64 v[220:221], v[174:175], 0, s[48:49]
	s_add_u32 m0, s98, 0xa000
	s_nop 0
	global_load_lds_dwordx4 v[220:221], off
	s_add_u32 s48, s96, s82
	s_addc_u32 s49, s97, s83
	v_lshl_add_u64 v[220:221], v[176:177], 0, s[48:49]
	s_add_u32 m0, s98, 0x4000
	s_nop 0
	global_load_lds_dwordx4 v[220:221], off
	s_add_u32 s48, s96, 0x5a0080
	s_addc_u32 s49, s97, 0
	v_lshl_add_u64 v[220:221], v[174:175], 0, s[48:49]
	s_add_u32 m0, s98, 0xc000
	s_nop 0
	global_load_lds_dwordx4 v[220:221], off
	s_add_u32 s48, s96, 0x2c91080
	s_addc_u32 s49, s97, 0
	v_lshl_add_u64 v[220:221], v[176:177], 0, s[48:49]
	s_add_u32 m0, s98, 0x6000
	s_nop 0
	global_load_lds_dwordx4 v[220:221], off
	s_add_u32 s48, s96, 0x5c0080
	s_addc_u32 s49, s97, 0
	v_lshl_add_u64 v[220:221], v[174:175], 0, s[48:49]
	s_add_u32 m0, s98, 0xe000
	s_nop 0
	global_load_lds_dwordx4 v[220:221], off
	.p2align 6
